# v20 + first K-loop iteration of each GEMM unit peeled with C=0 MFMAs (128 accumulator-zeroing v_mov per unit removed)
# speedup vs baseline: 1.0175x; 1.0011x over previous
; #define PG8_STAGE(bufoff, gbase, voff) do { _Pragma("unroll") for (int _i = 0; _i < 2; ++_i) \
;         __builtin_amdgcn_global_load_lds((const unsigned*)((const char*)(gbase) + (voff)[_i]), (PG8_LAS unsigned*)(lds + (bufoff) + ldsw + _i * 8192), 16, 0, 0); } while (0)
; #define PG8_LDA(dst, b, h) do { _Pragma("unroll") for (int m = 0; m < 4; ++m) _Pragma("unroll") for (int k = 0; k < 2; ++k) dst[m][k] = *(const PG8_LAS bf16x8*)(lds + PG8_SA(b, h) + aoff + m * 2048 + k * 1024); } while (0)
; #define PG8_WAIT_V(n) asm volatile("s_waitcnt vmcnt(" #n ")" ::: "memory")
; #define PG8_WAIT_L(n) asm volatile("s_waitcnt lgkmcnt(" #n ")" ::: "memory")
; template <class Epi, class Sched, bool ALIGN_EPI = false, bool SP2 = false>
; __device__ __forceinline__ void gemm_phase(PG8_LAS unsigned char* lds, const int tid, const Gemm g, const Sched& S, const Epi& E) {
;     ...
;         const bool has_next = S.next(ui + 1, nxt);
;         const char* nA = has_next ? (const char*)g.A + (size_t)nxt.pm * tstep : cA; const char* nB = has_next ? (const char*)g.Bt + (size_t)nxt.pn * tstep + (size_t)(nxt.pm >> 5) * g.bstride : cB;
;         for (int t = 0; t < nt; t += 2) {
;             const bool last = (t == nt - 2);
;             const char* a1 = cA + (size_t)(t + 1) * kstep;
;             const char* a2 = last ? nA : cA + (size_t)(t + 2) * kstep; const char* b2 = last ? nB : cB + (size_t)(t + 2) * kstep;
;             const char* a3 = a2 + kstep; const char* b3 = b2 + kstep;
;             if (last && has_next) S.a_ready(nxt);
;             if constexpr (SP2) {
;             PG8_LDB(B0, 0, 0); PG8_LDB(B1, 0, 1); PG8_SCHED; PG8_LDA(At, 0, 0); PG8_STAGE(PG8_SA(1, 1), a1 + hstep, voffA);
;             PG8_WAIT_V(8); PG8_WAIT_L(0); PG8_BAR; PG8_MMA(0, 0, At, B0); PG8_MMA(0, 1, At, B1); PG8_BAR; PG8_SCHED;
;             PG8_LDA(At, 0, 1); PG8_STAGE(PG8_SB(0, 0), b2, voffB); PG8_STAGE(PG8_SB(0, 1), b2 + hstep, voffB); PG8_STAGE(PG8_SA(0, 0), a2, voffA);
;             PG8_WAIT_V(8); PG8_WAIT_L(0); PG8_BAR; PG8_MMA(1, 0, At, B0); PG8_MMA(1, 1, At, B1); PG8_BAR; PG8_SCHED;
;     ...
; #pragma unroll
;         for (int a = 0; a < 2; ++a)
; #pragma unroll
;             for (int b = 0; b < 2; ++b)
; #pragma unroll
;                 for (int m = 0; m < 4; ++m)
; #pragma unroll
;                     for (int n = 0; n < 2; ++n) acc[a][b][m][n] = (f32x4){0.f, 0.f, 0.f, 0.f};
.LBB0_129:
	s_ashr_i32 s55, s54, 31
	s_lshl_b64 s[26:27], s[54:55], 19
	v_readlane_b32 s60, v251, 16
	v_readlane_b32 s61, v251, 17
	s_add_u32 s58, s60, s26
	s_addc_u32 s59, s61, s27
	s_and_b64 s[4:5], s[4:5], exec
	s_cselect_b32 s26, s59, s3
	s_cselect_b32 s27, s58, s2
	s_add_u32 s2, s2, 0x40080
	s_addc_u32 s3, s3, 0
	s_add_u32 s38, s24, 0x100
	s_addc_u32 s39, s25, 0
	s_mov_b32 s41, -2
	v_readlane_b32 s62, v251, 18
	v_readlane_b32 s63, v251, 19
	s_add_u32 s4, s2, 0xfffc0080
	s_addc_u32 s5, s3, -1
	s_cmp_eq_u32 s41, 12
	s_cselect_b32 s25, s26, s5
	s_cselect_b32 s24, s27, s4
	s_cselect_b32 s5, s57, s39
	s_cselect_b32 s4, s56, s38
	ds_read_b128 v[48:51], v243
	ds_read_b128 v[52:55], v244
	ds_read_b128 v[56:59], v243 offset:2048
	ds_read_b128 v[60:63], v244 offset:2048
	ds_read_b128 v[80:83], v243 offset:16384
	ds_read_b128 v[84:87], v244 offset:16384
	ds_read_b128 v[88:91], v243 offset:18432
	ds_read_b128 v[92:95], v244 offset:18432
	s_add_i32 m0, s17, 0xc000
	ds_read_b128 v[194:197], v204
	ds_read_b128 v[206:209], v242
	ds_read_b128 v[210:213], v204 offset:2048
	ds_read_b128 v[214:217], v242 offset:2048
	ds_read_b128 v[218:221], v204 offset:4096
	ds_read_b128 v[230:233], v242 offset:4096
	ds_read_b128 v[234:237], v204 offset:6144
	ds_read_b128 v[238:241], v242 offset:6144
	global_load_lds_dwordx4 v190, s[2:3]
	s_add_i32 m0, s17, 0xe000
	s_nop 0
	global_load_lds_dwordx4 v192, s[2:3]
	s_waitcnt vmcnt(8)
	s_waitcnt lgkmcnt(0)
	s_barrier
	s_setprio 1
	s_waitcnt lgkmcnt(0)
	v_mfma_f32_16x16x32_bf16 v[156:159], v[48:51], v[194:197], 0
	v_mfma_f32_16x16x32_bf16 v[152:155], v[56:59], v[194:197], 0
	v_mfma_f32_16x16x32_bf16 v[140:143], v[48:51], v[210:213], 0
	v_mfma_f32_16x16x32_bf16 v[136:139], v[56:59], v[210:213], 0
	v_mfma_f32_16x16x32_bf16 v[124:127], v[48:51], v[218:221], 0
	v_mfma_f32_16x16x32_bf16 v[120:123], v[56:59], v[218:221], 0
	v_mfma_f32_16x16x32_bf16 v[108:111], v[48:51], v[234:237], 0
	v_mfma_f32_16x16x32_bf16 v[104:107], v[56:59], v[234:237], 0
	v_mfma_f32_16x16x32_bf16 v[156:159], v[52:55], v[206:209], v[156:159]
	v_mfma_f32_16x16x32_bf16 v[152:155], v[60:63], v[206:209], v[152:155]
	v_mfma_f32_16x16x32_bf16 v[140:143], v[52:55], v[214:217], v[140:143]
	v_mfma_f32_16x16x32_bf16 v[136:139], v[60:63], v[214:217], v[136:139]
	v_mfma_f32_16x16x32_bf16 v[124:127], v[52:55], v[230:233], v[124:127]
	v_mfma_f32_16x16x32_bf16 v[120:123], v[60:63], v[230:233], v[120:123]
	v_mfma_f32_16x16x32_bf16 v[108:111], v[52:55], v[238:241], v[108:111]
	v_mfma_f32_16x16x32_bf16 v[104:107], v[60:63], v[238:241], v[104:107]
	s_setprio 0
	s_setprio 1
	v_mfma_f32_16x16x32_bf16 v[148:151], v[80:83], v[194:197], 0
	v_mfma_f32_16x16x32_bf16 v[144:147], v[88:91], v[194:197], 0
	v_mfma_f32_16x16x32_bf16 v[132:135], v[80:83], v[210:213], 0
	v_mfma_f32_16x16x32_bf16 v[128:131], v[88:91], v[210:213], 0
	v_mfma_f32_16x16x32_bf16 v[116:119], v[80:83], v[218:221], 0
	v_mfma_f32_16x16x32_bf16 v[112:115], v[88:91], v[218:221], 0
	v_mfma_f32_16x16x32_bf16 v[100:103], v[80:83], v[234:237], 0
	v_mfma_f32_16x16x32_bf16 v[96:99], v[88:91], v[234:237], 0
	v_mfma_f32_16x16x32_bf16 v[148:151], v[84:87], v[206:209], v[148:151]
	v_mfma_f32_16x16x32_bf16 v[144:147], v[92:95], v[206:209], v[144:147]
	v_mfma_f32_16x16x32_bf16 v[132:135], v[84:87], v[214:217], v[132:135]
	v_mfma_f32_16x16x32_bf16 v[128:131], v[92:95], v[214:217], v[128:131]
	v_mfma_f32_16x16x32_bf16 v[116:119], v[84:87], v[230:233], v[116:119]
	v_mfma_f32_16x16x32_bf16 v[112:115], v[92:95], v[230:233], v[112:115]
	v_mfma_f32_16x16x32_bf16 v[100:103], v[84:87], v[238:241], v[100:103]
	v_mfma_f32_16x16x32_bf16 v[96:99], v[92:95], v[238:241], v[96:99]
	s_setprio 0
	s_barrier
	s_add_i32 m0, s16, 0x10000
	ds_read_b128 v[194:197], v204 offset:16384
	ds_read_b128 v[206:209], v242 offset:16384
	ds_read_b128 v[210:213], v204 offset:18432
	ds_read_b128 v[214:217], v242 offset:18432
	ds_read_b128 v[218:221], v204 offset:20480
	ds_read_b128 v[230:233], v242 offset:20480
	ds_read_b128 v[234:237], v204 offset:22528
	ds_read_b128 v[238:241], v242 offset:22528
	global_load_lds_dwordx4 v164, s[4:5]
	s_add_i32 m0, s16, 0x12000
	s_add_u32 s60, s4, 0x40000
	s_addc_u32 s61, s5, 0
	global_load_lds_dwordx4 v160, s[4:5]
	s_add_i32 m0, s16, 0x14000
	s_nop 0
	global_load_lds_dwordx4 v164, s[60:61]
	s_add_i32 m0, s16, 0x16000
	s_nop 0
	global_load_lds_dwordx4 v160, s[60:61]
	s_mov_b32 m0, s17
	s_nop 0
	global_load_lds_dwordx4 v166, s[24:25]
	s_mov_b32 m0, s18
	s_nop 0
	global_load_lds_dwordx4 v162, s[24:25]
	s_waitcnt vmcnt(8)
	s_waitcnt lgkmcnt(0)
	s_barrier
	s_setprio 1
	s_waitcnt lgkmcnt(0)
	v_mfma_f32_16x16x32_bf16 v[76:79], v[48:51], v[194:197], 0
	v_mfma_f32_16x16x32_bf16 v[72:75], v[56:59], v[194:197], 0
	v_mfma_f32_16x16x32_bf16 v[44:47], v[48:51], v[210:213], 0
	v_mfma_f32_16x16x32_bf16 v[40:43], v[56:59], v[210:213], 0
	v_mfma_f32_16x16x32_bf16 v[28:31], v[48:51], v[218:221], 0
	v_mfma_f32_16x16x32_bf16 v[24:27], v[56:59], v[218:221], 0
	v_mfma_f32_16x16x32_bf16 v[12:15], v[48:51], v[234:237], 0
	v_mfma_f32_16x16x32_bf16 v[8:11], v[56:59], v[234:237], 0
	v_mfma_f32_16x16x32_bf16 v[76:79], v[52:55], v[206:209], v[76:79]
	v_mfma_f32_16x16x32_bf16 v[72:75], v[60:63], v[206:209], v[72:75]
	v_mfma_f32_16x16x32_bf16 v[44:47], v[52:55], v[214:217], v[44:47]
	v_mfma_f32_16x16x32_bf16 v[40:43], v[60:63], v[214:217], v[40:43]
	v_mfma_f32_16x16x32_bf16 v[28:31], v[52:55], v[230:233], v[28:31]
	v_mfma_f32_16x16x32_bf16 v[24:27], v[60:63], v[230:233], v[24:27]
	v_mfma_f32_16x16x32_bf16 v[12:15], v[52:55], v[238:241], v[12:15]
	v_mfma_f32_16x16x32_bf16 v[8:11], v[60:63], v[238:241], v[8:11]
	s_setprio 0
	s_setprio 1
	v_mfma_f32_16x16x32_bf16 v[36:39], v[80:83], v[210:213], 0
	v_mfma_f32_16x16x32_bf16 v[32:35], v[88:91], v[210:213], 0
	v_mfma_f32_16x16x32_bf16 v[20:23], v[80:83], v[218:221], 0
	v_mfma_f32_16x16x32_bf16 v[16:19], v[88:91], v[218:221], 0
	v_mfma_f32_16x16x32_bf16 v[4:7], v[80:83], v[234:237], 0
	v_mfma_f32_16x16x32_bf16 v[0:3], v[88:91], v[234:237], 0
	v_mfma_f32_16x16x32_bf16 v[48:51], v[80:83], v[194:197], 0
	v_mfma_f32_16x16x32_bf16 v[52:55], v[88:91], v[194:197], 0
	v_mfma_f32_16x16x32_bf16 v[36:39], v[84:87], v[214:217], v[36:39]
	v_mfma_f32_16x16x32_bf16 v[32:35], v[92:95], v[214:217], v[32:35]
	v_mfma_f32_16x16x32_bf16 v[20:23], v[84:87], v[230:233], v[20:23]
	v_mfma_f32_16x16x32_bf16 v[16:19], v[92:95], v[230:233], v[16:19]
	v_mfma_f32_16x16x32_bf16 v[4:7], v[84:87], v[238:241], v[4:7]
	v_mfma_f32_16x16x32_bf16 v[0:3], v[92:95], v[238:241], v[0:3]
	v_mfma_f32_16x16x32_bf16 v[48:51], v[84:87], v[206:209], v[48:51]
	v_mfma_f32_16x16x32_bf16 v[52:55], v[92:95], v[206:209], v[52:55]
	s_setprio 0
	s_barrier
; #define PG8_STAGE(bufoff, gbase, voff) do { _Pragma("unroll") for (int _i = 0; _i < 2; ++_i) \
;         __builtin_amdgcn_global_load_lds((const unsigned*)((const char*)(gbase) + (voff)[_i]), (PG8_LAS unsigned*)(lds + (bufoff) + ldsw + _i * 8192), 16, 0, 0); } while (0)
; #define PG8_LDA(dst, b, h) do { _Pragma("unroll") for (int m = 0; m < 4; ++m) _Pragma("unroll") for (int k = 0; k < 2; ++k) dst[m][k] = *(const PG8_LAS bf16x8*)(lds + PG8_SA(b, h) + aoff + m * 2048 + k * 1024); } while (0)
; #define PG8_LDB(dst, b, h) do { _Pragma("unroll") for (int n = 0; n < 2; ++n) _Pragma("unroll") for (int k = 0; k < 2; ++k) dst[n][k] = *(const PG8_LAS bf16x8*)(lds + PG8_SB(b, h) + boff + n * 2048 + k * 1024); } while (0)
; #define PG8_MMA(ai, bj, At, Bt) do { __builtin_amdgcn_s_setprio(1); _Pragma("unroll") for (int m = 0; m < 4; ++m) _Pragma("unroll") for (int n = 0; n < 2; ++n) _Pragma("unroll") for (int k = 0; k < 2; ++k) \
;         acc[ai][bj][m][n] = __builtin_amdgcn_mfma_f32_16x16x32_bf16(Bt[n][k], At[m][k], acc[ai][bj][m][n], 0, 0, 0); __builtin_amdgcn_s_setprio(0); } while (0)
; #define PG8_WAIT_V(n) asm volatile("s_waitcnt vmcnt(" #n ")" ::: "memory")
; #define PG8_WAIT_L(n) asm volatile("s_waitcnt lgkmcnt(" #n ")" ::: "memory")
; #define PG8_BAR __builtin_amdgcn_s_barrier()
; #define PG8_SCHED __builtin_amdgcn_sched_barrier(0)
; template <class Epi, class Sched, bool ALIGN_EPI = false, bool SP2 = false>
; __device__ __forceinline__ void gemm_phase(PG8_LAS unsigned char* lds, const int tid, const Gemm g, const Sched& S, const Epi& E) {
;     ...
;             PG8_LDB(B0, 1, 0); PG8_LDB(B1, 1, 1); PG8_SCHED; PG8_LDA(At, 1, 0); PG8_STAGE(PG8_SA(0, 1), a2 + hstep, voffA);
;             PG8_WAIT_V(8); PG8_WAIT_L(0); PG8_BAR; PG8_MMA(0, 0, At, B0); PG8_MMA(0, 1, At, B1); PG8_BAR; PG8_SCHED;
;             PG8_LDA(At, 1, 1); PG8_STAGE(PG8_SB(1, 0), b3, voffB); PG8_STAGE(PG8_SB(1, 1), b3 + hstep, voffB); PG8_STAGE(PG8_SA(1, 0), a3, voffA);
;             PG8_WAIT_V(8); PG8_WAIT_L(0); PG8_BAR; PG8_MMA(1, 0, At, B0); PG8_MMA(1, 1, At, B1); PG8_BAR; PG8_SCHED;
	ds_read_b128 v[56:59], v243 offset:32768
	ds_read_b128 v[60:63], v244 offset:32768
	ds_read_b128 v[64:67], v243 offset:34816
	ds_read_b128 v[68:71], v244 offset:34816
	ds_read_b128 v[80:83], v243 offset:49152
	ds_read_b128 v[84:87], v244 offset:49152
	ds_read_b128 v[88:91], v243 offset:51200
	ds_read_b128 v[92:95], v244 offset:51200
	s_add_u32 s24, s24, 0x40000
	s_addc_u32 s25, s25, 0
	s_mov_b32 m0, s19
	ds_read_b128 v[194:197], v204 offset:32768
	ds_read_b128 v[206:209], v242 offset:32768
	ds_read_b128 v[210:213], v204 offset:34816
	ds_read_b128 v[214:217], v242 offset:34816
	ds_read_b128 v[218:221], v204 offset:36864
	ds_read_b128 v[230:233], v242 offset:36864
	ds_read_b128 v[234:237], v204 offset:38912
	ds_read_b128 v[238:241], v242 offset:38912
	global_load_lds_dwordx4 v166, s[24:25]
	s_mov_b32 m0, s20
	s_nop 0
	global_load_lds_dwordx4 v162, s[24:25]
	s_waitcnt vmcnt(8)
	s_waitcnt lgkmcnt(0)
	s_barrier
	s_setprio 1
	s_waitcnt lgkmcnt(0)
	v_mfma_f32_16x16x32_bf16 v[156:159], v[56:59], v[194:197], v[156:159]
	v_mfma_f32_16x16x32_bf16 v[152:155], v[64:67], v[194:197], v[152:155]
	v_mfma_f32_16x16x32_bf16 v[140:143], v[56:59], v[210:213], v[140:143]
	v_mfma_f32_16x16x32_bf16 v[136:139], v[64:67], v[210:213], v[136:139]
	v_mfma_f32_16x16x32_bf16 v[124:127], v[56:59], v[218:221], v[124:127]
	v_mfma_f32_16x16x32_bf16 v[120:123], v[64:67], v[218:221], v[120:123]
	v_mfma_f32_16x16x32_bf16 v[108:111], v[56:59], v[234:237], v[108:111]
	v_mfma_f32_16x16x32_bf16 v[104:107], v[64:67], v[234:237], v[104:107]
	v_mfma_f32_16x16x32_bf16 v[156:159], v[60:63], v[206:209], v[156:159]
	v_mfma_f32_16x16x32_bf16 v[152:155], v[68:71], v[206:209], v[152:155]
	v_mfma_f32_16x16x32_bf16 v[140:143], v[60:63], v[214:217], v[140:143]
	v_mfma_f32_16x16x32_bf16 v[136:139], v[68:71], v[214:217], v[136:139]
	v_mfma_f32_16x16x32_bf16 v[124:127], v[60:63], v[230:233], v[124:127]
	v_mfma_f32_16x16x32_bf16 v[120:123], v[68:71], v[230:233], v[120:123]
	v_mfma_f32_16x16x32_bf16 v[108:111], v[60:63], v[238:241], v[108:111]
	v_mfma_f32_16x16x32_bf16 v[104:107], v[68:71], v[238:241], v[104:107]
	s_setprio 0
	s_setprio 1
	v_mfma_f32_16x16x32_bf16 v[148:151], v[80:83], v[194:197], v[148:151]
	v_mfma_f32_16x16x32_bf16 v[144:147], v[88:91], v[194:197], v[144:147]
	v_mfma_f32_16x16x32_bf16 v[132:135], v[80:83], v[210:213], v[132:135]
	v_mfma_f32_16x16x32_bf16 v[128:131], v[88:91], v[210:213], v[128:131]
	v_mfma_f32_16x16x32_bf16 v[116:119], v[80:83], v[218:221], v[116:119]
	v_mfma_f32_16x16x32_bf16 v[112:115], v[88:91], v[218:221], v[112:115]
	v_mfma_f32_16x16x32_bf16 v[100:103], v[80:83], v[234:237], v[100:103]
	v_mfma_f32_16x16x32_bf16 v[96:99], v[88:91], v[234:237], v[96:99]
	v_mfma_f32_16x16x32_bf16 v[148:151], v[84:87], v[206:209], v[148:151]
	v_mfma_f32_16x16x32_bf16 v[144:147], v[92:95], v[206:209], v[144:147]
	v_mfma_f32_16x16x32_bf16 v[132:135], v[84:87], v[214:217], v[132:135]
	v_mfma_f32_16x16x32_bf16 v[128:131], v[92:95], v[214:217], v[128:131]
	v_mfma_f32_16x16x32_bf16 v[116:119], v[84:87], v[230:233], v[116:119]
	v_mfma_f32_16x16x32_bf16 v[112:115], v[92:95], v[230:233], v[112:115]
	v_mfma_f32_16x16x32_bf16 v[100:103], v[84:87], v[238:241], v[100:103]
	v_mfma_f32_16x16x32_bf16 v[96:99], v[92:95], v[238:241], v[96:99]
	s_setprio 0
	s_barrier
	s_add_u32 s94, s4, 0x80
	s_addc_u32 s95, s5, 0
	s_add_i32 m0, s16, 0x18000
	ds_read_b128 v[194:197], v204 offset:49152
	ds_read_b128 v[206:209], v242 offset:49152
	ds_read_b128 v[210:213], v204 offset:51200
	ds_read_b128 v[214:217], v242 offset:51200
	ds_read_b128 v[218:221], v204 offset:53248
	ds_read_b128 v[230:233], v242 offset:53248
	ds_read_b128 v[234:237], v204 offset:55296
	ds_read_b128 v[238:241], v242 offset:55296
	global_load_lds_dwordx4 v164, s[94:95]
	s_add_i32 m0, s16, 0x1a000
	s_add_u32 s4, s4, 0x40080
	s_addc_u32 s5, s5, 0
	global_load_lds_dwordx4 v160, s[94:95]
	s_add_i32 m0, s16, 0x1c000
	s_add_u32 s92, s24, 0xfffc0080
	s_addc_u32 s93, s25, -1
	global_load_lds_dwordx4 v164, s[4:5]
	s_add_i32 m0, s16, 0x1e000
	s_nop 0
	global_load_lds_dwordx4 v160, s[4:5]
	s_mov_b32 m0, s66
	s_nop 0
	global_load_lds_dwordx4 v166, s[92:93]
	s_mov_b32 m0, s67
	s_nop 0
	global_load_lds_dwordx4 v162, s[92:93]
	s_waitcnt vmcnt(8)
	s_waitcnt lgkmcnt(0)
	s_barrier
	s_setprio 1
	s_waitcnt lgkmcnt(0)
	v_mfma_f32_16x16x32_bf16 v[76:79], v[56:59], v[194:197], v[76:79]
	v_mfma_f32_16x16x32_bf16 v[72:75], v[64:67], v[194:197], v[72:75]
	v_mfma_f32_16x16x32_bf16 v[44:47], v[56:59], v[210:213], v[44:47]
	v_mfma_f32_16x16x32_bf16 v[40:43], v[64:67], v[210:213], v[40:43]
	v_mfma_f32_16x16x32_bf16 v[28:31], v[56:59], v[218:221], v[28:31]
	v_mfma_f32_16x16x32_bf16 v[24:27], v[64:67], v[218:221], v[24:27]
	v_mfma_f32_16x16x32_bf16 v[12:15], v[56:59], v[234:237], v[12:15]
	v_mfma_f32_16x16x32_bf16 v[8:11], v[64:67], v[234:237], v[8:11]
	v_mfma_f32_16x16x32_bf16 v[76:79], v[60:63], v[206:209], v[76:79]
	v_mfma_f32_16x16x32_bf16 v[72:75], v[68:71], v[206:209], v[72:75]
	v_mfma_f32_16x16x32_bf16 v[44:47], v[60:63], v[214:217], v[44:47]
	v_mfma_f32_16x16x32_bf16 v[40:43], v[68:71], v[214:217], v[40:43]
	v_mfma_f32_16x16x32_bf16 v[28:31], v[60:63], v[230:233], v[28:31]
	v_mfma_f32_16x16x32_bf16 v[24:27], v[68:71], v[230:233], v[24:27]
	v_mfma_f32_16x16x32_bf16 v[12:15], v[60:63], v[238:241], v[12:15]
	v_mfma_f32_16x16x32_bf16 v[8:11], v[68:71], v[238:241], v[8:11]
	s_setprio 0
	s_setprio 1
	v_mfma_f32_16x16x32_bf16 v[48:51], v[80:83], v[194:197], v[48:51]
	v_mfma_f32_16x16x32_bf16 v[68:71], v[84:87], v[206:209], v[48:51]
	v_mfma_f32_16x16x32_bf16 v[48:51], v[88:91], v[194:197], v[52:55]
	v_mfma_f32_16x16x32_bf16 v[36:39], v[80:83], v[210:213], v[36:39]
	v_mfma_f32_16x16x32_bf16 v[32:35], v[88:91], v[210:213], v[32:35]
	v_mfma_f32_16x16x32_bf16 v[20:23], v[80:83], v[218:221], v[20:23]
	v_mfma_f32_16x16x32_bf16 v[16:19], v[88:91], v[218:221], v[16:19]
	v_mfma_f32_16x16x32_bf16 v[4:7], v[80:83], v[234:237], v[4:7]
	v_mfma_f32_16x16x32_bf16 v[0:3], v[88:91], v[234:237], v[0:3]
	v_mfma_f32_16x16x32_bf16 v[64:67], v[92:95], v[206:209], v[48:51]
	v_mfma_f32_16x16x32_bf16 v[36:39], v[84:87], v[214:217], v[36:39]
	v_mfma_f32_16x16x32_bf16 v[32:35], v[92:95], v[214:217], v[32:35]
	v_mfma_f32_16x16x32_bf16 v[20:23], v[84:87], v[230:233], v[20:23]
	v_mfma_f32_16x16x32_bf16 v[16:19], v[92:95], v[230:233], v[16:19]
	v_mfma_f32_16x16x32_bf16 v[4:7], v[84:87], v[238:241], v[4:7]
	v_mfma_f32_16x16x32_bf16 v[0:3], v[92:95], v[238:241], v[0:3]
	s_setprio 0
	s_barrier
	s_add_i32 s41, s41, 2
	s_add_u32 s2, s2, 0x100
	s_addc_u32 s3, s3, 0
	s_add_u32 s38, s38, 0x100
	s_addc_u32 s39, s39, 0
	s_cmp_gt_u32 s41, 13
	s_cbranch_scc0 .LBB0_130
	s_branch .Lpeel_exit_g1

; #define PG8_BAR __builtin_amdgcn_s_barrier()
; template <class Epi, class Sched, bool ALIGN_EPI = false, bool SP2 = false>
; __device__ __forceinline__ void gemm_phase(PG8_LAS unsigned char* lds, const int tid, const Gemm g, const Sched& S, const Epi& E) {
;     ...
;         }
;         if constexpr (ALIGN_EPI) { if (wr == 0) PG8_BAR; }
.Lpeel_exit_g1:
	s_and_b64 vcc, exec, s[50:51]
	s_cbranch_vccz .LBB0_133
	s_barrier

; #define PG8_STAGE(bufoff, gbase, voff) do { _Pragma("unroll") for (int _i = 0; _i < 2; ++_i) \
;         __builtin_amdgcn_global_load_lds((const unsigned*)((const char*)(gbase) + (voff)[_i]), (PG8_LAS unsigned*)(lds + (bufoff) + ldsw + _i * 8192), 16, 0, 0); } while (0)
; #define PG8_LDA(dst, b, h) do { _Pragma("unroll") for (int m = 0; m < 4; ++m) _Pragma("unroll") for (int k = 0; k < 2; ++k) dst[m][k] = *(const PG8_LAS bf16x8*)(lds + PG8_SA(b, h) + aoff + m * 2048 + k * 1024); } while (0)
; #define PG8_LDB(dst, b, h) do { _Pragma("unroll") for (int n = 0; n < 2; ++n) _Pragma("unroll") for (int k = 0; k < 2; ++k) dst[n][k] = *(const PG8_LAS bf16x8*)(lds + PG8_SB(b, h) + boff + n * 2048 + k * 1024); } while (0)
; #define PG8_MMA(ai, bj, At, Bt) do { __builtin_amdgcn_s_setprio(1); _Pragma("unroll") for (int m = 0; m < 4; ++m) _Pragma("unroll") for (int n = 0; n < 2; ++n) _Pragma("unroll") for (int k = 0; k < 2; ++k) \
;         acc[ai][bj][m][n] = __builtin_amdgcn_mfma_f32_16x16x32_bf16(Bt[n][k], At[m][k], acc[ai][bj][m][n], 0, 0, 0); __builtin_amdgcn_s_setprio(0); } while (0)
; #define PG8_WAIT_V(n) asm volatile("s_waitcnt vmcnt(" #n ")" ::: "memory")
; #define PG8_WAIT_L(n) asm volatile("s_waitcnt lgkmcnt(" #n ")" ::: "memory")
; #define PG8_BAR __builtin_amdgcn_s_barrier()
; #define PG8_SCHED __builtin_amdgcn_sched_barrier(0)
; template <class Epi, class Sched, bool ALIGN_EPI = false, bool SP2 = false>
; __device__ __forceinline__ void gemm_phase(PG8_LAS unsigned char* lds, const int tid, const Gemm g, const Sched& S, const Epi& E) {
;     ...
;             PG8_LDB(B0, 0, 0); PG8_LDB(B1, 0, 1); PG8_SCHED; PG8_LDA(At, 0, 0); PG8_STAGE(PG8_SA(1, 1), a1 + hstep, voffA);
;             PG8_WAIT_V(8); PG8_WAIT_L(0); PG8_BAR; PG8_MMA(0, 0, At, B0); PG8_MMA(0, 1, At, B1); PG8_BAR; PG8_SCHED;
;             PG8_LDA(At, 0, 1); PG8_STAGE(PG8_SB(0, 0), b2, voffB); PG8_STAGE(PG8_SB(0, 1), b2 + hstep, voffB); PG8_STAGE(PG8_SA(0, 0), a2, voffA);
;             PG8_WAIT_V(8); PG8_WAIT_L(0); PG8_BAR; PG8_MMA(1, 0, At, B0); PG8_MMA(1, 1, At, B1); PG8_BAR; PG8_SCHED;
.LBB0_310:
	s_add_u32 s38, s26, 0x80
	s_addc_u32 s39, s27, 0
	s_add_u32 s26, s24, 0x100
	s_addc_u32 s27, s25, 0
	s_mov_b32 s14, 0
	s_waitcnt lgkmcnt(0)
	s_add_i32 s51, s14, 2
	s_add_u32 s10, s38, 0x80
	s_addc_u32 s24, s39, 0
	s_cmp_eq_u32 s47, s14
	s_cselect_b32 s25, s29, s24
	s_cselect_b32 s24, s28, s10
	s_cselect_b32 s53, s43, s27
	s_cselect_b32 s52, s42, s26
	s_add_u32 s92, s38, s12
	s_addc_u32 s93, s39, 0
	ds_read_b128 v[72:75], v247
	ds_read_b128 v[76:79], v248
	ds_read_b128 v[136:139], v247 offset:2048
	ds_read_b128 v[140:143], v248 offset:2048
	ds_read_b128 v[144:147], v247 offset:16384
	ds_read_b128 v[148:151], v248 offset:16384
	ds_read_b128 v[152:155], v247 offset:18432
	ds_read_b128 v[156:159], v248 offset:18432
	s_add_i32 m0, s20, 0xc000
	ds_read_b128 v[160:163], v232
	ds_read_b128 v[164:167], v246
	ds_read_b128 v[196:199], v232 offset:2048
	ds_read_b128 v[200:203], v246 offset:2048
	ds_read_b128 v[204:207], v232 offset:4096
	ds_read_b128 v[208:211], v246 offset:4096
	ds_read_b128 v[212:215], v232 offset:6144
	ds_read_b128 v[216:219], v246 offset:6144
	global_load_lds_dwordx4 v190, s[92:93]
	s_add_i32 m0, s20, 0xe000
	s_nop 0
	global_load_lds_dwordx4 v188, s[92:93]
	s_waitcnt vmcnt(8)
	s_waitcnt lgkmcnt(0)
	s_barrier
	s_setprio 1
	s_waitcnt lgkmcnt(0)
	v_mfma_f32_16x16x32_bf16 v[132:135], v[72:75], v[160:163], 0
	v_mfma_f32_16x16x32_bf16 v[128:131], v[136:139], v[160:163], 0
	v_mfma_f32_16x16x32_bf16 v[116:119], v[72:75], v[196:199], 0
	v_mfma_f32_16x16x32_bf16 v[112:115], v[136:139], v[196:199], 0
	v_mfma_f32_16x16x32_bf16 v[100:103], v[72:75], v[204:207], 0
	v_mfma_f32_16x16x32_bf16 v[96:99], v[136:139], v[204:207], 0
	v_mfma_f32_16x16x32_bf16 v[84:87], v[72:75], v[212:215], 0
	v_mfma_f32_16x16x32_bf16 v[80:83], v[136:139], v[212:215], 0
	v_mfma_f32_16x16x32_bf16 v[132:135], v[76:79], v[164:167], v[132:135]
	v_mfma_f32_16x16x32_bf16 v[128:131], v[140:143], v[164:167], v[128:131]
	v_mfma_f32_16x16x32_bf16 v[116:119], v[76:79], v[200:203], v[116:119]
	v_mfma_f32_16x16x32_bf16 v[112:115], v[140:143], v[200:203], v[112:115]
	v_mfma_f32_16x16x32_bf16 v[100:103], v[76:79], v[208:211], v[100:103]
	v_mfma_f32_16x16x32_bf16 v[96:99], v[140:143], v[208:211], v[96:99]
	v_mfma_f32_16x16x32_bf16 v[84:87], v[76:79], v[216:219], v[84:87]
	v_mfma_f32_16x16x32_bf16 v[80:83], v[140:143], v[216:219], v[80:83]
	s_setprio 0
	s_setprio 1
	v_mfma_f32_16x16x32_bf16 v[124:127], v[144:147], v[160:163], 0
	v_mfma_f32_16x16x32_bf16 v[120:123], v[152:155], v[160:163], 0
	v_mfma_f32_16x16x32_bf16 v[108:111], v[144:147], v[196:199], 0
	v_mfma_f32_16x16x32_bf16 v[104:107], v[152:155], v[196:199], 0
	v_mfma_f32_16x16x32_bf16 v[92:95], v[144:147], v[204:207], 0
	v_mfma_f32_16x16x32_bf16 v[88:91], v[152:155], v[204:207], 0
	v_mfma_f32_16x16x32_bf16 v[68:71], v[144:147], v[212:215], 0
	v_mfma_f32_16x16x32_bf16 v[64:67], v[152:155], v[212:215], 0
	v_mfma_f32_16x16x32_bf16 v[124:127], v[148:151], v[164:167], v[124:127]
	v_mfma_f32_16x16x32_bf16 v[120:123], v[156:159], v[164:167], v[120:123]
	v_mfma_f32_16x16x32_bf16 v[108:111], v[148:151], v[200:203], v[108:111]
	v_mfma_f32_16x16x32_bf16 v[104:107], v[156:159], v[200:203], v[104:107]
	v_mfma_f32_16x16x32_bf16 v[92:95], v[148:151], v[208:211], v[92:95]
	v_mfma_f32_16x16x32_bf16 v[88:91], v[156:159], v[208:211], v[88:91]
	v_mfma_f32_16x16x32_bf16 v[68:71], v[148:151], v[216:219], v[68:71]
	v_mfma_f32_16x16x32_bf16 v[64:67], v[156:159], v[216:219], v[64:67]
	s_setprio 0
	s_barrier
	s_add_i32 m0, s15, 0x10000
	ds_read_b128 v[160:163], v232 offset:16384
	ds_read_b128 v[164:167], v246 offset:16384
	ds_read_b128 v[196:199], v232 offset:18432
	ds_read_b128 v[200:203], v246 offset:18432
	ds_read_b128 v[204:207], v232 offset:20480
	ds_read_b128 v[208:211], v246 offset:20480
	ds_read_b128 v[212:215], v232 offset:22528
	ds_read_b128 v[216:219], v246 offset:22528
	global_load_lds_dwordx4 v168, s[52:53]
	s_add_i32 m0, s15, 0x12000
	s_add_u32 s94, s52, 0x80
	s_addc_u32 s95, s53, 0
	global_load_lds_dwordx4 v186, s[52:53]
	s_add_u32 s52, s52, s12
	s_addc_u32 s53, s53, 0
	s_add_i32 m0, s15, 0x14000
	s_add_u32 s98, s24, 0x80
	s_addc_u32 s99, s25, 0
	global_load_lds_dwordx4 v168, s[52:53]
	s_add_i32 m0, s15, 0x16000
	s_nop 0
	global_load_lds_dwordx4 v186, s[52:53]
	s_mov_b32 m0, s20
	s_nop 0
	global_load_lds_dwordx4 v190, s[24:25]
	s_mov_b32 m0, s21
	s_nop 0
	global_load_lds_dwordx4 v188, s[24:25]
	s_waitcnt vmcnt(8)
	s_waitcnt lgkmcnt(0)
	s_barrier
	s_setprio 1
	s_waitcnt lgkmcnt(0)
	v_mfma_f32_16x16x32_bf16 v[60:63], v[72:75], v[160:163], 0
	v_mfma_f32_16x16x32_bf16 v[56:59], v[136:139], v[160:163], 0
	v_mfma_f32_16x16x32_bf16 v[44:47], v[72:75], v[196:199], 0
	v_mfma_f32_16x16x32_bf16 v[40:43], v[136:139], v[196:199], 0
	v_mfma_f32_16x16x32_bf16 v[28:31], v[72:75], v[204:207], 0
	v_mfma_f32_16x16x32_bf16 v[24:27], v[136:139], v[204:207], 0
	v_mfma_f32_16x16x32_bf16 v[12:15], v[72:75], v[212:215], 0
	v_mfma_f32_16x16x32_bf16 v[8:11], v[136:139], v[212:215], 0
	v_mfma_f32_16x16x32_bf16 v[60:63], v[76:79], v[164:167], v[60:63]
	v_mfma_f32_16x16x32_bf16 v[56:59], v[140:143], v[164:167], v[56:59]
	v_mfma_f32_16x16x32_bf16 v[44:47], v[76:79], v[200:203], v[44:47]
	v_mfma_f32_16x16x32_bf16 v[40:43], v[140:143], v[200:203], v[40:43]
	v_mfma_f32_16x16x32_bf16 v[28:31], v[76:79], v[208:211], v[28:31]
	v_mfma_f32_16x16x32_bf16 v[24:27], v[140:143], v[208:211], v[24:27]
	v_mfma_f32_16x16x32_bf16 v[12:15], v[76:79], v[216:219], v[12:15]
	v_mfma_f32_16x16x32_bf16 v[8:11], v[140:143], v[216:219], v[8:11]
	s_setprio 0
	s_setprio 1
	v_mfma_f32_16x16x32_bf16 v[52:55], v[144:147], v[160:163], 0
	v_mfma_f32_16x16x32_bf16 v[48:51], v[152:155], v[160:163], 0
	v_mfma_f32_16x16x32_bf16 v[36:39], v[144:147], v[196:199], 0
	v_mfma_f32_16x16x32_bf16 v[32:35], v[152:155], v[196:199], 0
	v_mfma_f32_16x16x32_bf16 v[20:23], v[144:147], v[204:207], 0
	v_mfma_f32_16x16x32_bf16 v[16:19], v[152:155], v[204:207], 0
	v_mfma_f32_16x16x32_bf16 v[4:7], v[144:147], v[212:215], 0
	v_mfma_f32_16x16x32_bf16 v[0:3], v[152:155], v[212:215], 0
	v_mfma_f32_16x16x32_bf16 v[52:55], v[148:151], v[164:167], v[52:55]
	v_mfma_f32_16x16x32_bf16 v[48:51], v[156:159], v[164:167], v[48:51]
	v_mfma_f32_16x16x32_bf16 v[36:39], v[148:151], v[200:203], v[36:39]
	v_mfma_f32_16x16x32_bf16 v[32:35], v[156:159], v[200:203], v[32:35]
	v_mfma_f32_16x16x32_bf16 v[20:23], v[148:151], v[208:211], v[20:23]
	v_mfma_f32_16x16x32_bf16 v[16:19], v[156:159], v[208:211], v[16:19]
	v_mfma_f32_16x16x32_bf16 v[4:7], v[148:151], v[216:219], v[4:7]
	v_mfma_f32_16x16x32_bf16 v[0:3], v[156:159], v[216:219], v[0:3]
	s_setprio 0
	s_barrier
; #define PG8_STAGE(bufoff, gbase, voff) do { _Pragma("unroll") for (int _i = 0; _i < 2; ++_i) \
;         __builtin_amdgcn_global_load_lds((const unsigned*)((const char*)(gbase) + (voff)[_i]), (PG8_LAS unsigned*)(lds + (bufoff) + ldsw + _i * 8192), 16, 0, 0); } while (0)
; #define PG8_LDA(dst, b, h) do { _Pragma("unroll") for (int m = 0; m < 4; ++m) _Pragma("unroll") for (int k = 0; k < 2; ++k) dst[m][k] = *(const PG8_LAS bf16x8*)(lds + PG8_SA(b, h) + aoff + m * 2048 + k * 1024); } while (0)
; #define PG8_LDB(dst, b, h) do { _Pragma("unroll") for (int n = 0; n < 2; ++n) _Pragma("unroll") for (int k = 0; k < 2; ++k) dst[n][k] = *(const PG8_LAS bf16x8*)(lds + PG8_SB(b, h) + boff + n * 2048 + k * 1024); } while (0)
; #define PG8_MMA(ai, bj, At, Bt) do { __builtin_amdgcn_s_setprio(1); _Pragma("unroll") for (int m = 0; m < 4; ++m) _Pragma("unroll") for (int n = 0; n < 2; ++n) _Pragma("unroll") for (int k = 0; k < 2; ++k) \
;         acc[ai][bj][m][n] = __builtin_amdgcn_mfma_f32_16x16x32_bf16(Bt[n][k], At[m][k], acc[ai][bj][m][n], 0, 0, 0); __builtin_amdgcn_s_setprio(0); } while (0)
; #define PG8_WAIT_V(n) asm volatile("s_waitcnt vmcnt(" #n ")" ::: "memory")
; #define PG8_WAIT_L(n) asm volatile("s_waitcnt lgkmcnt(" #n ")" ::: "memory")
; #define PG8_BAR __builtin_amdgcn_s_barrier()
; #define PG8_SCHED __builtin_amdgcn_sched_barrier(0)
; template <class Epi, class Sched, bool ALIGN_EPI = false, bool SP2 = false>
; __device__ __forceinline__ void gemm_phase(PG8_LAS unsigned char* lds, const int tid, const Gemm g, const Sched& S, const Epi& E) {
;     ...
;             PG8_LDB(B0, 1, 0); PG8_LDB(B1, 1, 1); PG8_SCHED; PG8_LDA(At, 1, 0); PG8_STAGE(PG8_SA(0, 1), a2 + hstep, voffA);
;             PG8_WAIT_V(8); PG8_WAIT_L(0); PG8_BAR; PG8_MMA(0, 0, At, B0); PG8_MMA(0, 1, At, B1); PG8_BAR; PG8_SCHED;
;             PG8_LDA(At, 1, 1); PG8_STAGE(PG8_SB(1, 0), b3, voffB); PG8_STAGE(PG8_SB(1, 1), b3 + hstep, voffB); PG8_STAGE(PG8_SA(1, 0), a3, voffA);
;             PG8_WAIT_V(8); PG8_WAIT_L(0); PG8_BAR; PG8_MMA(1, 0, At, B0); PG8_MMA(1, 1, At, B1); PG8_BAR; PG8_SCHED;
	ds_read_b128 v[72:75], v247 offset:32768
	ds_read_b128 v[76:79], v248 offset:32768
	ds_read_b128 v[136:139], v247 offset:34816
	ds_read_b128 v[140:143], v248 offset:34816
	ds_read_b128 v[144:147], v247 offset:49152
	ds_read_b128 v[148:151], v248 offset:49152
	ds_read_b128 v[152:155], v247 offset:51200
	ds_read_b128 v[156:159], v248 offset:51200
	s_add_u32 s24, s24, s12
	s_addc_u32 s25, s25, 0
	s_mov_b32 m0, s22
	ds_read_b128 v[160:163], v232 offset:32768
	ds_read_b128 v[164:167], v246 offset:32768
	ds_read_b128 v[196:199], v232 offset:34816
	ds_read_b128 v[200:203], v246 offset:34816
	ds_read_b128 v[204:207], v232 offset:36864
	ds_read_b128 v[208:211], v246 offset:36864
	ds_read_b128 v[212:215], v232 offset:38912
	ds_read_b128 v[216:219], v246 offset:38912
	global_load_lds_dwordx4 v190, s[24:25]
	s_mov_b32 m0, s23
	s_nop 0
	global_load_lds_dwordx4 v188, s[24:25]
	s_waitcnt vmcnt(8)
	s_waitcnt lgkmcnt(0)
	s_barrier
	s_setprio 1
	s_waitcnt lgkmcnt(0)
	v_mfma_f32_16x16x32_bf16 v[132:135], v[72:75], v[160:163], v[132:135]
	v_mfma_f32_16x16x32_bf16 v[128:131], v[136:139], v[160:163], v[128:131]
	v_mfma_f32_16x16x32_bf16 v[116:119], v[72:75], v[196:199], v[116:119]
	v_mfma_f32_16x16x32_bf16 v[112:115], v[136:139], v[196:199], v[112:115]
	v_mfma_f32_16x16x32_bf16 v[100:103], v[72:75], v[204:207], v[100:103]
	v_mfma_f32_16x16x32_bf16 v[96:99], v[136:139], v[204:207], v[96:99]
	v_mfma_f32_16x16x32_bf16 v[84:87], v[72:75], v[212:215], v[84:87]
	v_mfma_f32_16x16x32_bf16 v[80:83], v[136:139], v[212:215], v[80:83]
	v_mfma_f32_16x16x32_bf16 v[132:135], v[76:79], v[164:167], v[132:135]
	v_mfma_f32_16x16x32_bf16 v[128:131], v[140:143], v[164:167], v[128:131]
	v_mfma_f32_16x16x32_bf16 v[116:119], v[76:79], v[200:203], v[116:119]
	v_mfma_f32_16x16x32_bf16 v[112:115], v[140:143], v[200:203], v[112:115]
	v_mfma_f32_16x16x32_bf16 v[100:103], v[76:79], v[208:211], v[100:103]
	v_mfma_f32_16x16x32_bf16 v[96:99], v[140:143], v[208:211], v[96:99]
	v_mfma_f32_16x16x32_bf16 v[84:87], v[76:79], v[216:219], v[84:87]
	v_mfma_f32_16x16x32_bf16 v[80:83], v[140:143], v[216:219], v[80:83]
	s_setprio 0
	s_setprio 1
	v_mfma_f32_16x16x32_bf16 v[124:127], v[144:147], v[160:163], v[124:127]
	v_mfma_f32_16x16x32_bf16 v[120:123], v[152:155], v[160:163], v[120:123]
	v_mfma_f32_16x16x32_bf16 v[108:111], v[144:147], v[196:199], v[108:111]
	v_mfma_f32_16x16x32_bf16 v[104:107], v[152:155], v[196:199], v[104:107]
	v_mfma_f32_16x16x32_bf16 v[92:95], v[144:147], v[204:207], v[92:95]
	v_mfma_f32_16x16x32_bf16 v[88:91], v[152:155], v[204:207], v[88:91]
	v_mfma_f32_16x16x32_bf16 v[68:71], v[144:147], v[212:215], v[68:71]
	v_mfma_f32_16x16x32_bf16 v[64:67], v[152:155], v[212:215], v[64:67]
	v_mfma_f32_16x16x32_bf16 v[124:127], v[148:151], v[164:167], v[124:127]
	v_mfma_f32_16x16x32_bf16 v[120:123], v[156:159], v[164:167], v[120:123]
	v_mfma_f32_16x16x32_bf16 v[108:111], v[148:151], v[200:203], v[108:111]
	v_mfma_f32_16x16x32_bf16 v[104:107], v[156:159], v[200:203], v[104:107]
	v_mfma_f32_16x16x32_bf16 v[92:95], v[148:151], v[208:211], v[92:95]
	v_mfma_f32_16x16x32_bf16 v[88:91], v[156:159], v[208:211], v[88:91]
	v_mfma_f32_16x16x32_bf16 v[68:71], v[148:151], v[216:219], v[68:71]
	v_mfma_f32_16x16x32_bf16 v[64:67], v[156:159], v[216:219], v[64:67]
	s_setprio 0
	s_barrier
	s_add_u32 s96, s52, 0x80
	s_addc_u32 s97, s53, 0
	s_add_i32 m0, s15, 0x18000
	ds_read_b128 v[160:163], v232 offset:49152
	ds_read_b128 v[164:167], v246 offset:49152
	ds_read_b128 v[196:199], v232 offset:51200
	ds_read_b128 v[200:203], v246 offset:51200
	ds_read_b128 v[204:207], v232 offset:53248
	ds_read_b128 v[208:211], v246 offset:53248
	ds_read_b128 v[212:215], v232 offset:55296
	ds_read_b128 v[216:219], v246 offset:55296
	global_load_lds_dwordx4 v168, s[94:95]
	s_add_i32 m0, s15, 0x1a000
	s_nop 0
	global_load_lds_dwordx4 v186, s[94:95]
	s_add_i32 m0, s15, 0x1c000
	s_nop 0
	global_load_lds_dwordx4 v168, s[96:97]
	s_add_i32 m0, s15, 0x1e000
	s_nop 0
	global_load_lds_dwordx4 v186, s[96:97]
	s_mov_b32 m0, s45
	s_nop 0
	global_load_lds_dwordx4 v190, s[98:99]
	s_mov_b32 m0, s46
	s_nop 0
	global_load_lds_dwordx4 v188, s[98:99]
	s_waitcnt vmcnt(8)
	s_waitcnt lgkmcnt(0)
	s_barrier
	s_setprio 1
	s_waitcnt lgkmcnt(0)
	v_mfma_f32_16x16x32_bf16 v[60:63], v[72:75], v[160:163], v[60:63]
	v_mfma_f32_16x16x32_bf16 v[56:59], v[136:139], v[160:163], v[56:59]
	v_mfma_f32_16x16x32_bf16 v[44:47], v[72:75], v[196:199], v[44:47]
	v_mfma_f32_16x16x32_bf16 v[40:43], v[136:139], v[196:199], v[40:43]
	v_mfma_f32_16x16x32_bf16 v[28:31], v[72:75], v[204:207], v[28:31]
	v_mfma_f32_16x16x32_bf16 v[24:27], v[136:139], v[204:207], v[24:27]
	v_mfma_f32_16x16x32_bf16 v[12:15], v[72:75], v[212:215], v[12:15]
	v_mfma_f32_16x16x32_bf16 v[8:11], v[136:139], v[212:215], v[8:11]
	v_mfma_f32_16x16x32_bf16 v[60:63], v[76:79], v[164:167], v[60:63]
	v_mfma_f32_16x16x32_bf16 v[56:59], v[140:143], v[164:167], v[56:59]
	v_mfma_f32_16x16x32_bf16 v[44:47], v[76:79], v[200:203], v[44:47]
	v_mfma_f32_16x16x32_bf16 v[40:43], v[140:143], v[200:203], v[40:43]
	v_mfma_f32_16x16x32_bf16 v[28:31], v[76:79], v[208:211], v[28:31]
	v_mfma_f32_16x16x32_bf16 v[24:27], v[140:143], v[208:211], v[24:27]
	v_mfma_f32_16x16x32_bf16 v[12:15], v[76:79], v[216:219], v[12:15]
	v_mfma_f32_16x16x32_bf16 v[8:11], v[140:143], v[216:219], v[8:11]
	s_setprio 0
	s_setprio 1
	v_mfma_f32_16x16x32_bf16 v[52:55], v[144:147], v[160:163], v[52:55]
	v_mfma_f32_16x16x32_bf16 v[48:51], v[152:155], v[160:163], v[48:51]
	v_mfma_f32_16x16x32_bf16 v[36:39], v[144:147], v[196:199], v[36:39]
	v_mfma_f32_16x16x32_bf16 v[32:35], v[152:155], v[196:199], v[32:35]
	v_mfma_f32_16x16x32_bf16 v[20:23], v[144:147], v[204:207], v[20:23]
	v_mfma_f32_16x16x32_bf16 v[16:19], v[152:155], v[204:207], v[16:19]
	v_mfma_f32_16x16x32_bf16 v[4:7], v[144:147], v[212:215], v[4:7]
	v_mfma_f32_16x16x32_bf16 v[0:3], v[152:155], v[212:215], v[0:3]
	v_mfma_f32_16x16x32_bf16 v[52:55], v[148:151], v[164:167], v[52:55]
	v_mfma_f32_16x16x32_bf16 v[48:51], v[156:159], v[164:167], v[48:51]
	v_mfma_f32_16x16x32_bf16 v[36:39], v[148:151], v[200:203], v[36:39]
	v_mfma_f32_16x16x32_bf16 v[32:35], v[156:159], v[200:203], v[32:35]
	v_mfma_f32_16x16x32_bf16 v[20:23], v[148:151], v[208:211], v[20:23]
	v_mfma_f32_16x16x32_bf16 v[16:19], v[156:159], v[208:211], v[16:19]
	v_mfma_f32_16x16x32_bf16 v[4:7], v[148:151], v[216:219], v[4:7]
	v_mfma_f32_16x16x32_bf16 v[0:3], v[156:159], v[216:219], v[0:3]
	s_setprio 0
	s_barrier
	s_add_u32 s38, s38, 0x100
	s_addc_u32 s39, s39, 0
	s_add_u32 s26, s26, 0x100
	s_addc_u32 s27, s27, 0
	s_cmp_ge_u32 s51, s44
	s_mov_b32 s14, s51
	s_cbranch_scc0 .LBB0_311
	s_branch .Lpeel_exit_g2

; #define PG8_BAR __builtin_amdgcn_s_barrier()
; template <class Epi, class Sched, bool ALIGN_EPI = false, bool SP2 = false>
; __device__ __forceinline__ void gemm_phase(PG8_LAS unsigned char* lds, const int tid, const Gemm g, const Sched& S, const Epi& E) {
;     ...
;         if constexpr (ALIGN_EPI) { if (wr == 0) PG8_BAR; }
;         if constexpr (!Epi::AFTER_DRAIN) { E(acc, cur, wr, wc, fr, fq); S.done(cur); }
.Lpeel_exit_g2:
	s_and_b64 vcc, exec, s[6:7]
	s_cbranch_vccz .LBB0_314
	s_barrier

; #define PG8_STAGE(bufoff, gbase, voff) do { _Pragma("unroll") for (int _i = 0; _i < 2; ++_i) \
;         __builtin_amdgcn_global_load_lds((const unsigned*)((const char*)(gbase) + (voff)[_i]), (PG8_LAS unsigned*)(lds + (bufoff) + ldsw + _i * 8192), 16, 0, 0); } while (0)
; #define PG8_LDA(dst, b, h) do { _Pragma("unroll") for (int m = 0; m < 4; ++m) _Pragma("unroll") for (int k = 0; k < 2; ++k) dst[m][k] = *(const PG8_LAS bf16x8*)(lds + PG8_SA(b, h) + aoff + m * 2048 + k * 1024); } while (0)
; #define PG8_LDB(dst, b, h) do { _Pragma("unroll") for (int n = 0; n < 2; ++n) _Pragma("unroll") for (int k = 0; k < 2; ++k) dst[n][k] = *(const PG8_LAS bf16x8*)(lds + PG8_SB(b, h) + boff + n * 2048 + k * 1024); } while (0)
; #define PG8_WAIT_V(n) asm volatile("s_waitcnt vmcnt(" #n ")" ::: "memory")
; #define PG8_WAIT_L(n) asm volatile("s_waitcnt lgkmcnt(" #n ")" ::: "memory")
; #define PG8_BAR __builtin_amdgcn_s_barrier()
; #define PG8_SCHED __builtin_amdgcn_sched_barrier(0)
; template <class Epi, class Sched, bool ALIGN_EPI = false, bool SP2 = false>
; __device__ __forceinline__ void gemm_phase(PG8_LAS unsigned char* lds, const int tid, const Gemm g, const Sched& S, const Epi& E) {
;     ...
;         const char* nA = has_next ? (const char*)g.A + (size_t)nxt.pm * tstep : cA; const char* nB = has_next ? (const char*)g.Bt + (size_t)nxt.pn * tstep + (size_t)(nxt.pm >> 5) * g.bstride : cB;
;         for (int t = 0; t < nt; t += 2) {
;             const bool last = (t == nt - 2);
;             const char* a1 = cA + (size_t)(t + 1) * kstep;
;             const char* a2 = last ? nA : cA + (size_t)(t + 2) * kstep; const char* b2 = last ? nB : cB + (size_t)(t + 2) * kstep;
;             const char* a3 = a2 + kstep; const char* b3 = b2 + kstep;
;             if (last && has_next) S.a_ready(nxt);
;             if constexpr (SP2) {
;             PG8_LDB(B0, 0, 0); PG8_LDB(B1, 0, 1); PG8_SCHED; PG8_LDA(At, 0, 0); PG8_STAGE(PG8_SA(1, 1), a1 + hstep, voffA);
;             PG8_WAIT_V(8); PG8_WAIT_L(0); PG8_BAR; PG8_MMA(0, 0, At, B0); PG8_MMA(0, 1, At, B1); PG8_BAR; PG8_SCHED;
;             PG8_LDA(At, 0, 1); PG8_STAGE(PG8_SB(0, 0), b2, voffB); PG8_STAGE(PG8_SB(0, 1), b2 + hstep, voffB); PG8_STAGE(PG8_SA(0, 0), a2, voffA);
;             PG8_WAIT_V(8); PG8_WAIT_L(0); PG8_BAR; PG8_MMA(1, 0, At, B0); PG8_MMA(1, 1, At, B1); PG8_BAR; PG8_SCHED;
.LBB0_425:
	s_ashr_i32 s41, s40, 31
	s_lshl_b64 s[44:45], s[40:41], 19
	v_readlane_b32 s48, v251, 16
	v_readlane_b32 s49, v251, 17
	s_add_u32 s44, s48, s44
	s_addc_u32 s45, s49, s45
	s_and_b64 s[4:5], s[4:5], exec
	s_cselect_b32 s39, s45, s27
	s_cselect_b32 s41, s44, s26
	s_add_u32 s4, s26, 0x40080
	s_addc_u32 s5, s27, 0
	s_add_u32 s46, s24, 0x100
	s_addc_u32 s47, s25, 0
	s_mov_b32 s48, -2
	v_readlane_b32 s50, v251, 18
	v_readlane_b32 s51, v251, 19
	s_add_u32 s24, s4, 0xfffc0080
	s_addc_u32 s25, s5, -1
	s_cmp_eq_u32 s48, 12
	s_cselect_b32 s27, s39, s25
	s_cselect_b32 s26, s41, s24
	s_cselect_b32 s25, s43, s47
	s_cselect_b32 s24, s42, s46
	ds_read_b128 v[64:67], v244
	ds_read_b128 v[68:71], v245
	ds_read_b128 v[72:75], v244 offset:2048
	ds_read_b128 v[76:79], v245 offset:2048
	ds_read_b128 v[154:157], v244 offset:16384
	ds_read_b128 v[164:167], v245 offset:16384
	ds_read_b128 v[186:189], v244 offset:18432
	ds_read_b128 v[190:193], v245 offset:18432
	s_add_i32 m0, s14, 0xc000
	ds_read_b128 v[194:197], v161
	ds_read_b128 v[198:201], v249
	ds_read_b128 v[202:205], v161 offset:2048
	ds_read_b128 v[206:209], v249 offset:2048
	ds_read_b128 v[210:213], v161 offset:4096
	ds_read_b128 v[214:217], v249 offset:4096
	ds_read_b128 v[218:221], v161 offset:6144
	ds_read_b128 v[230:233], v249 offset:6144
	global_load_lds_dwordx4 v150, s[4:5]
	s_add_i32 m0, s14, 0xe000
	s_nop 0
	global_load_lds_dwordx4 v152, s[4:5]
	s_waitcnt vmcnt(8)
	s_waitcnt lgkmcnt(0)
	s_barrier
	s_setprio 1
	s_waitcnt lgkmcnt(0)
	v_mfma_f32_16x16x32_bf16 v[140:143], v[64:67], v[194:197], 0
	v_mfma_f32_16x16x32_bf16 v[136:139], v[72:75], v[194:197], 0
	v_mfma_f32_16x16x32_bf16 v[124:127], v[64:67], v[202:205], 0
	v_mfma_f32_16x16x32_bf16 v[120:123], v[72:75], v[202:205], 0
	v_mfma_f32_16x16x32_bf16 v[108:111], v[64:67], v[210:213], 0
	v_mfma_f32_16x16x32_bf16 v[104:107], v[72:75], v[210:213], 0
	v_mfma_f32_16x16x32_bf16 v[92:95], v[64:67], v[218:221], 0
	v_mfma_f32_16x16x32_bf16 v[88:91], v[72:75], v[218:221], 0
	v_mfma_f32_16x16x32_bf16 v[140:143], v[68:71], v[198:201], v[140:143]
	v_mfma_f32_16x16x32_bf16 v[136:139], v[76:79], v[198:201], v[136:139]
	v_mfma_f32_16x16x32_bf16 v[124:127], v[68:71], v[206:209], v[124:127]
	v_mfma_f32_16x16x32_bf16 v[120:123], v[76:79], v[206:209], v[120:123]
	v_mfma_f32_16x16x32_bf16 v[108:111], v[68:71], v[214:217], v[108:111]
	v_mfma_f32_16x16x32_bf16 v[104:107], v[76:79], v[214:217], v[104:107]
	v_mfma_f32_16x16x32_bf16 v[92:95], v[68:71], v[230:233], v[92:95]
	v_mfma_f32_16x16x32_bf16 v[88:91], v[76:79], v[230:233], v[88:91]
	s_setprio 0
	s_setprio 1
	v_mfma_f32_16x16x32_bf16 v[132:135], v[154:157], v[194:197], 0
	v_mfma_f32_16x16x32_bf16 v[128:131], v[186:189], v[194:197], 0
	v_mfma_f32_16x16x32_bf16 v[116:119], v[154:157], v[202:205], 0
	v_mfma_f32_16x16x32_bf16 v[112:115], v[186:189], v[202:205], 0
	v_mfma_f32_16x16x32_bf16 v[100:103], v[154:157], v[210:213], 0
	v_mfma_f32_16x16x32_bf16 v[96:99], v[186:189], v[210:213], 0
	v_mfma_f32_16x16x32_bf16 v[84:87], v[154:157], v[218:221], 0
	v_mfma_f32_16x16x32_bf16 v[80:83], v[186:189], v[218:221], 0
	v_mfma_f32_16x16x32_bf16 v[132:135], v[164:167], v[198:201], v[132:135]
	v_mfma_f32_16x16x32_bf16 v[128:131], v[190:193], v[198:201], v[128:131]
	v_mfma_f32_16x16x32_bf16 v[116:119], v[164:167], v[206:209], v[116:119]
	v_mfma_f32_16x16x32_bf16 v[112:115], v[190:193], v[206:209], v[112:115]
	v_mfma_f32_16x16x32_bf16 v[100:103], v[164:167], v[214:217], v[100:103]
	v_mfma_f32_16x16x32_bf16 v[96:99], v[190:193], v[214:217], v[96:99]
	v_mfma_f32_16x16x32_bf16 v[84:87], v[164:167], v[230:233], v[84:87]
	v_mfma_f32_16x16x32_bf16 v[80:83], v[190:193], v[230:233], v[80:83]
	s_setprio 0
	s_barrier
	s_add_i32 m0, s12, 0x10000
	ds_read_b128 v[194:197], v161 offset:16384
	ds_read_b128 v[198:201], v249 offset:16384
	ds_read_b128 v[202:205], v161 offset:18432
	ds_read_b128 v[206:209], v249 offset:18432
	ds_read_b128 v[210:213], v161 offset:20480
	ds_read_b128 v[214:217], v249 offset:20480
	ds_read_b128 v[218:221], v161 offset:22528
	ds_read_b128 v[230:233], v249 offset:22528
	global_load_lds_dwordx4 v168, s[24:25]
	s_add_i32 m0, s12, 0x12000
	s_add_u32 s50, s24, 0x40000
	s_addc_u32 s51, s25, 0
	global_load_lds_dwordx4 v144, s[24:25]
	s_add_i32 m0, s12, 0x14000
	s_nop 0
	global_load_lds_dwordx4 v168, s[50:51]
	s_add_i32 m0, s12, 0x16000
	s_nop 0
	global_load_lds_dwordx4 v144, s[50:51]
	s_mov_b32 m0, s14
	s_nop 0
	global_load_lds_dwordx4 v148, s[26:27]
	s_mov_b32 m0, s15
	s_nop 0
	global_load_lds_dwordx4 v146, s[26:27]
	s_waitcnt vmcnt(8)
	s_waitcnt lgkmcnt(0)
	s_barrier
; #define PG8_STAGE(bufoff, gbase, voff) do { _Pragma("unroll") for (int _i = 0; _i < 2; ++_i) \
;         __builtin_amdgcn_global_load_lds((const unsigned*)((const char*)(gbase) + (voff)[_i]), (PG8_LAS unsigned*)(lds + (bufoff) + ldsw + _i * 8192), 16, 0, 0); } while (0)
; #define PG8_LDA(dst, b, h) do { _Pragma("unroll") for (int m = 0; m < 4; ++m) _Pragma("unroll") for (int k = 0; k < 2; ++k) dst[m][k] = *(const PG8_LAS bf16x8*)(lds + PG8_SA(b, h) + aoff + m * 2048 + k * 1024); } while (0)
; #define PG8_LDB(dst, b, h) do { _Pragma("unroll") for (int n = 0; n < 2; ++n) _Pragma("unroll") for (int k = 0; k < 2; ++k) dst[n][k] = *(const PG8_LAS bf16x8*)(lds + PG8_SB(b, h) + boff + n * 2048 + k * 1024); } while (0)
; #define PG8_MMA(ai, bj, At, Bt) do { __builtin_amdgcn_s_setprio(1); _Pragma("unroll") for (int m = 0; m < 4; ++m) _Pragma("unroll") for (int n = 0; n < 2; ++n) _Pragma("unroll") for (int k = 0; k < 2; ++k) \
;         acc[ai][bj][m][n] = __builtin_amdgcn_mfma_f32_16x16x32_bf16(Bt[n][k], At[m][k], acc[ai][bj][m][n], 0, 0, 0); __builtin_amdgcn_s_setprio(0); } while (0)
; #define PG8_WAIT_V(n) asm volatile("s_waitcnt vmcnt(" #n ")" ::: "memory")
; #define PG8_WAIT_L(n) asm volatile("s_waitcnt lgkmcnt(" #n ")" ::: "memory")
; #define PG8_BAR __builtin_amdgcn_s_barrier()
; #define PG8_SCHED __builtin_amdgcn_sched_barrier(0)
; template <class Epi, class Sched, bool ALIGN_EPI = false, bool SP2 = false>
; __device__ __forceinline__ void gemm_phase(PG8_LAS unsigned char* lds, const int tid, const Gemm g, const Sched& S, const Epi& E) {
;     ...
;             PG8_WAIT_V(8); PG8_WAIT_L(0); PG8_BAR; PG8_MMA(1, 0, At, B0); PG8_MMA(1, 1, At, B1); PG8_BAR; PG8_SCHED;
;             PG8_LDB(B0, 1, 0); PG8_LDB(B1, 1, 1); PG8_SCHED; PG8_LDA(At, 1, 0); PG8_STAGE(PG8_SA(0, 1), a2 + hstep, voffA);
;             PG8_WAIT_V(8); PG8_WAIT_L(0); PG8_BAR; PG8_MMA(0, 0, At, B0); PG8_MMA(0, 1, At, B1); PG8_BAR; PG8_SCHED;
;             PG8_LDA(At, 1, 1); PG8_STAGE(PG8_SB(1, 0), b3, voffB); PG8_STAGE(PG8_SB(1, 1), b3 + hstep, voffB); PG8_STAGE(PG8_SA(1, 0), a3, voffA);
;             PG8_WAIT_V(8); PG8_WAIT_L(0); PG8_BAR; PG8_MMA(1, 0, At, B0); PG8_MMA(1, 1, At, B1); PG8_BAR; PG8_SCHED;
	s_setprio 1
	s_waitcnt lgkmcnt(0)
	v_mfma_f32_16x16x32_bf16 v[60:63], v[64:67], v[194:197], 0
	v_mfma_f32_16x16x32_bf16 v[56:59], v[72:75], v[194:197], 0
	v_mfma_f32_16x16x32_bf16 v[44:47], v[64:67], v[202:205], 0
	v_mfma_f32_16x16x32_bf16 v[40:43], v[72:75], v[202:205], 0
	v_mfma_f32_16x16x32_bf16 v[28:31], v[64:67], v[210:213], 0
	v_mfma_f32_16x16x32_bf16 v[24:27], v[72:75], v[210:213], 0
	v_mfma_f32_16x16x32_bf16 v[12:15], v[64:67], v[218:221], 0
	v_mfma_f32_16x16x32_bf16 v[8:11], v[72:75], v[218:221], 0
	v_mfma_f32_16x16x32_bf16 v[60:63], v[68:71], v[198:201], v[60:63]
	v_mfma_f32_16x16x32_bf16 v[56:59], v[76:79], v[198:201], v[56:59]
	v_mfma_f32_16x16x32_bf16 v[44:47], v[68:71], v[206:209], v[44:47]
	v_mfma_f32_16x16x32_bf16 v[40:43], v[76:79], v[206:209], v[40:43]
	v_mfma_f32_16x16x32_bf16 v[28:31], v[68:71], v[214:217], v[28:31]
	v_mfma_f32_16x16x32_bf16 v[24:27], v[76:79], v[214:217], v[24:27]
	v_mfma_f32_16x16x32_bf16 v[12:15], v[68:71], v[230:233], v[12:15]
	v_mfma_f32_16x16x32_bf16 v[8:11], v[76:79], v[230:233], v[8:11]
	s_setprio 0
	s_setprio 1
	v_mfma_f32_16x16x32_bf16 v[52:55], v[154:157], v[194:197], 0
	v_mfma_f32_16x16x32_bf16 v[48:51], v[186:189], v[194:197], 0
	v_mfma_f32_16x16x32_bf16 v[36:39], v[154:157], v[202:205], 0
	v_mfma_f32_16x16x32_bf16 v[32:35], v[186:189], v[202:205], 0
	v_mfma_f32_16x16x32_bf16 v[20:23], v[154:157], v[210:213], 0
	v_mfma_f32_16x16x32_bf16 v[16:19], v[186:189], v[210:213], 0
	v_mfma_f32_16x16x32_bf16 v[4:7], v[154:157], v[218:221], 0
	v_mfma_f32_16x16x32_bf16 v[0:3], v[186:189], v[218:221], 0
	v_mfma_f32_16x16x32_bf16 v[52:55], v[164:167], v[198:201], v[52:55]
	v_mfma_f32_16x16x32_bf16 v[48:51], v[190:193], v[198:201], v[48:51]
	v_mfma_f32_16x16x32_bf16 v[36:39], v[164:167], v[206:209], v[36:39]
	v_mfma_f32_16x16x32_bf16 v[32:35], v[190:193], v[206:209], v[32:35]
	v_mfma_f32_16x16x32_bf16 v[20:23], v[164:167], v[214:217], v[20:23]
	v_mfma_f32_16x16x32_bf16 v[16:19], v[190:193], v[214:217], v[16:19]
	v_mfma_f32_16x16x32_bf16 v[4:7], v[164:167], v[230:233], v[4:7]
	v_mfma_f32_16x16x32_bf16 v[0:3], v[190:193], v[230:233], v[0:3]
	s_setprio 0
	s_barrier
	ds_read_b128 v[64:67], v244 offset:32768
	ds_read_b128 v[68:71], v245 offset:32768
	ds_read_b128 v[72:75], v244 offset:34816
	ds_read_b128 v[76:79], v245 offset:34816
	ds_read_b128 v[154:157], v244 offset:49152
	ds_read_b128 v[164:167], v245 offset:49152
	ds_read_b128 v[186:189], v244 offset:51200
	ds_read_b128 v[190:193], v245 offset:51200
	s_add_u32 s26, s26, 0x40000
	s_addc_u32 s27, s27, 0
	s_mov_b32 m0, s16
	ds_read_b128 v[194:197], v161 offset:32768
	ds_read_b128 v[198:201], v249 offset:32768
	ds_read_b128 v[202:205], v161 offset:34816
	ds_read_b128 v[206:209], v249 offset:34816
	ds_read_b128 v[210:213], v161 offset:36864
	ds_read_b128 v[214:217], v249 offset:36864
	ds_read_b128 v[218:221], v161 offset:38912
	ds_read_b128 v[230:233], v249 offset:38912
	global_load_lds_dwordx4 v148, s[26:27]
	s_mov_b32 m0, s17
	s_nop 0
	global_load_lds_dwordx4 v146, s[26:27]
	s_waitcnt vmcnt(8)
	s_waitcnt lgkmcnt(0)
	s_barrier
	s_setprio 1
	s_waitcnt lgkmcnt(0)
	v_mfma_f32_16x16x32_bf16 v[140:143], v[64:67], v[194:197], v[140:143]
	v_mfma_f32_16x16x32_bf16 v[136:139], v[72:75], v[194:197], v[136:139]
	v_mfma_f32_16x16x32_bf16 v[124:127], v[64:67], v[202:205], v[124:127]
	v_mfma_f32_16x16x32_bf16 v[120:123], v[72:75], v[202:205], v[120:123]
	v_mfma_f32_16x16x32_bf16 v[108:111], v[64:67], v[210:213], v[108:111]
	v_mfma_f32_16x16x32_bf16 v[104:107], v[72:75], v[210:213], v[104:107]
	v_mfma_f32_16x16x32_bf16 v[92:95], v[64:67], v[218:221], v[92:95]
	v_mfma_f32_16x16x32_bf16 v[88:91], v[72:75], v[218:221], v[88:91]
	v_mfma_f32_16x16x32_bf16 v[140:143], v[68:71], v[198:201], v[140:143]
	v_mfma_f32_16x16x32_bf16 v[136:139], v[76:79], v[198:201], v[136:139]
	v_mfma_f32_16x16x32_bf16 v[124:127], v[68:71], v[206:209], v[124:127]
	v_mfma_f32_16x16x32_bf16 v[120:123], v[76:79], v[206:209], v[120:123]
	v_mfma_f32_16x16x32_bf16 v[108:111], v[68:71], v[214:217], v[108:111]
	v_mfma_f32_16x16x32_bf16 v[104:107], v[76:79], v[214:217], v[104:107]
	v_mfma_f32_16x16x32_bf16 v[92:95], v[68:71], v[230:233], v[92:95]
	v_mfma_f32_16x16x32_bf16 v[88:91], v[76:79], v[230:233], v[88:91]
	s_setprio 0
	s_setprio 1
	v_mfma_f32_16x16x32_bf16 v[132:135], v[154:157], v[194:197], v[132:135]
	v_mfma_f32_16x16x32_bf16 v[128:131], v[186:189], v[194:197], v[128:131]
	v_mfma_f32_16x16x32_bf16 v[116:119], v[154:157], v[202:205], v[116:119]
	v_mfma_f32_16x16x32_bf16 v[112:115], v[186:189], v[202:205], v[112:115]
	v_mfma_f32_16x16x32_bf16 v[100:103], v[154:157], v[210:213], v[100:103]
	v_mfma_f32_16x16x32_bf16 v[96:99], v[186:189], v[210:213], v[96:99]
	v_mfma_f32_16x16x32_bf16 v[84:87], v[154:157], v[218:221], v[84:87]
	v_mfma_f32_16x16x32_bf16 v[80:83], v[186:189], v[218:221], v[80:83]
	v_mfma_f32_16x16x32_bf16 v[132:135], v[164:167], v[198:201], v[132:135]
	v_mfma_f32_16x16x32_bf16 v[128:131], v[190:193], v[198:201], v[128:131]
	v_mfma_f32_16x16x32_bf16 v[116:119], v[164:167], v[206:209], v[116:119]
	v_mfma_f32_16x16x32_bf16 v[112:115], v[190:193], v[206:209], v[112:115]
	v_mfma_f32_16x16x32_bf16 v[100:103], v[164:167], v[214:217], v[100:103]
	v_mfma_f32_16x16x32_bf16 v[96:99], v[190:193], v[214:217], v[96:99]
	v_mfma_f32_16x16x32_bf16 v[84:87], v[164:167], v[230:233], v[84:87]
	v_mfma_f32_16x16x32_bf16 v[80:83], v[190:193], v[230:233], v[80:83]
	s_setprio 0
	s_barrier
; #define PG8_STAGE(bufoff, gbase, voff) do { _Pragma("unroll") for (int _i = 0; _i < 2; ++_i) \
;         __builtin_amdgcn_global_load_lds((const unsigned*)((const char*)(gbase) + (voff)[_i]), (PG8_LAS unsigned*)(lds + (bufoff) + ldsw + _i * 8192), 16, 0, 0); } while (0)
; #define PG8_LDA(dst, b, h) do { _Pragma("unroll") for (int m = 0; m < 4; ++m) _Pragma("unroll") for (int k = 0; k < 2; ++k) dst[m][k] = *(const PG8_LAS bf16x8*)(lds + PG8_SA(b, h) + aoff + m * 2048 + k * 1024); } while (0)
; #define PG8_MMA(ai, bj, At, Bt) do { __builtin_amdgcn_s_setprio(1); _Pragma("unroll") for (int m = 0; m < 4; ++m) _Pragma("unroll") for (int n = 0; n < 2; ++n) _Pragma("unroll") for (int k = 0; k < 2; ++k) \
;         acc[ai][bj][m][n] = __builtin_amdgcn_mfma_f32_16x16x32_bf16(Bt[n][k], At[m][k], acc[ai][bj][m][n], 0, 0, 0); __builtin_amdgcn_s_setprio(0); } while (0)
; #define PG8_WAIT_V(n) asm volatile("s_waitcnt vmcnt(" #n ")" ::: "memory")
; #define PG8_WAIT_L(n) asm volatile("s_waitcnt lgkmcnt(" #n ")" ::: "memory")
; #define PG8_BAR __builtin_amdgcn_s_barrier()
; #define PG8_SCHED __builtin_amdgcn_sched_barrier(0)
; template <class Epi, class Sched, bool ALIGN_EPI = false, bool SP2 = false>
; __device__ __forceinline__ void gemm_phase(PG8_LAS unsigned char* lds, const int tid, const Gemm g, const Sched& S, const Epi& E) {
;     ...
;         for (int t = 0; t < nt; t += 2) {
;     ...
;             PG8_LDA(At, 1, 1); PG8_STAGE(PG8_SB(1, 0), b3, voffB); PG8_STAGE(PG8_SB(1, 1), b3 + hstep, voffB); PG8_STAGE(PG8_SA(1, 0), a3, voffA);
;             PG8_WAIT_V(8); PG8_WAIT_L(0); PG8_BAR; PG8_MMA(1, 0, At, B0); PG8_MMA(1, 1, At, B1); PG8_BAR; PG8_SCHED;
	s_add_u32 s94, s24, 0x80
	s_addc_u32 s95, s25, 0
	s_add_i32 m0, s12, 0x18000
	ds_read_b128 v[194:197], v161 offset:49152
	ds_read_b128 v[198:201], v249 offset:49152
	ds_read_b128 v[202:205], v161 offset:51200
	ds_read_b128 v[206:209], v249 offset:51200
	ds_read_b128 v[210:213], v161 offset:53248
	ds_read_b128 v[214:217], v249 offset:53248
	ds_read_b128 v[218:221], v161 offset:55296
	ds_read_b128 v[230:233], v249 offset:55296
	global_load_lds_dwordx4 v168, s[94:95]
	s_add_i32 m0, s12, 0x1a000
	s_add_u32 s24, s24, 0x40080
	s_addc_u32 s25, s25, 0
	global_load_lds_dwordx4 v144, s[94:95]
	s_add_i32 m0, s12, 0x1c000
	s_add_u32 s92, s26, 0xfffc0080
	s_addc_u32 s93, s27, -1
	global_load_lds_dwordx4 v168, s[24:25]
	s_add_i32 m0, s12, 0x1e000
	s_nop 0
	global_load_lds_dwordx4 v144, s[24:25]
	s_mov_b32 m0, s18
	s_nop 0
	global_load_lds_dwordx4 v148, s[92:93]
	s_mov_b32 m0, s19
	s_nop 0
	global_load_lds_dwordx4 v146, s[92:93]
	s_waitcnt vmcnt(8)
	s_waitcnt lgkmcnt(0)
	s_barrier
	s_setprio 1
	s_waitcnt lgkmcnt(0)
	v_mfma_f32_16x16x32_bf16 v[60:63], v[64:67], v[194:197], v[60:63]
	v_mfma_f32_16x16x32_bf16 v[56:59], v[72:75], v[194:197], v[56:59]
	v_mfma_f32_16x16x32_bf16 v[44:47], v[64:67], v[202:205], v[44:47]
	v_mfma_f32_16x16x32_bf16 v[40:43], v[72:75], v[202:205], v[40:43]
	v_mfma_f32_16x16x32_bf16 v[28:31], v[64:67], v[210:213], v[28:31]
	v_mfma_f32_16x16x32_bf16 v[24:27], v[72:75], v[210:213], v[24:27]
	v_mfma_f32_16x16x32_bf16 v[12:15], v[64:67], v[218:221], v[12:15]
	v_mfma_f32_16x16x32_bf16 v[8:11], v[72:75], v[218:221], v[8:11]
	v_mfma_f32_16x16x32_bf16 v[60:63], v[68:71], v[198:201], v[60:63]
	v_mfma_f32_16x16x32_bf16 v[56:59], v[76:79], v[198:201], v[56:59]
	v_mfma_f32_16x16x32_bf16 v[44:47], v[68:71], v[206:209], v[44:47]
	v_mfma_f32_16x16x32_bf16 v[40:43], v[76:79], v[206:209], v[40:43]
	v_mfma_f32_16x16x32_bf16 v[28:31], v[68:71], v[214:217], v[28:31]
	v_mfma_f32_16x16x32_bf16 v[24:27], v[76:79], v[214:217], v[24:27]
	v_mfma_f32_16x16x32_bf16 v[12:15], v[68:71], v[230:233], v[12:15]
	v_mfma_f32_16x16x32_bf16 v[8:11], v[76:79], v[230:233], v[8:11]
	s_setprio 0
	s_setprio 1
	v_mfma_f32_16x16x32_bf16 v[52:55], v[154:157], v[194:197], v[52:55]
	v_mfma_f32_16x16x32_bf16 v[48:51], v[186:189], v[194:197], v[48:51]
	v_mfma_f32_16x16x32_bf16 v[36:39], v[154:157], v[202:205], v[36:39]
	v_mfma_f32_16x16x32_bf16 v[32:35], v[186:189], v[202:205], v[32:35]
	v_mfma_f32_16x16x32_bf16 v[20:23], v[154:157], v[210:213], v[20:23]
	v_mfma_f32_16x16x32_bf16 v[16:19], v[186:189], v[210:213], v[16:19]
	v_mfma_f32_16x16x32_bf16 v[4:7], v[154:157], v[218:221], v[4:7]
	v_mfma_f32_16x16x32_bf16 v[0:3], v[186:189], v[218:221], v[0:3]
	v_mfma_f32_16x16x32_bf16 v[52:55], v[164:167], v[198:201], v[52:55]
	v_mfma_f32_16x16x32_bf16 v[48:51], v[190:193], v[198:201], v[48:51]
	v_mfma_f32_16x16x32_bf16 v[36:39], v[164:167], v[206:209], v[36:39]
	v_mfma_f32_16x16x32_bf16 v[32:35], v[190:193], v[206:209], v[32:35]
	v_mfma_f32_16x16x32_bf16 v[20:23], v[164:167], v[214:217], v[20:23]
	v_mfma_f32_16x16x32_bf16 v[16:19], v[190:193], v[214:217], v[16:19]
	v_mfma_f32_16x16x32_bf16 v[4:7], v[164:167], v[230:233], v[4:7]
	v_mfma_f32_16x16x32_bf16 v[0:3], v[190:193], v[230:233], v[0:3]
	s_setprio 0
	s_barrier
	s_add_i32 s48, s48, 2
	s_add_u32 s4, s4, 0x100
	s_addc_u32 s5, s5, 0
	s_add_u32 s46, s46, 0x100
	s_addc_u32 s47, s47, 0
	s_cmp_gt_u32 s48, 13
	s_cbranch_scc0 .LBB0_426
	s_branch .Lpeel_exit_g3

; #define PG8_BAR __builtin_amdgcn_s_barrier()
; template <class Epi, class Sched, bool ALIGN_EPI = false, bool SP2 = false>
; __device__ __forceinline__ void gemm_phase(PG8_LAS unsigned char* lds, const int tid, const Gemm g, const Sched& S, const Epi& E) {
;     ...
;         if constexpr (ALIGN_EPI) { if (wr == 0) PG8_BAR; }
;         if constexpr (!Epi::AFTER_DRAIN) { E(acc, cur, wr, wc, fr, fq); S.done(cur); }
.Lpeel_exit_g3:
	s_and_b64 vcc, exec, s[28:29]
	s_cbranch_vccz .LBB0_429
	s_barrier
